# NSA selected phase B: K/V fragments read from fragment-major copies (written by vt_item into dead XB area) -> coalesced 1KiB loads
# speedup vs baseline: 1.0429x; 1.0429x over previous
.LBB0_549:
	s_or_b64 exec, exec, s[4:5]
	s_lshl_b32 s68, s52, 1
	s_lshl_b64 s[6:7], s[68:69], 2
	s_waitcnt lgkmcnt(0)
	s_barrier
	s_add_u32 s4, s66, s6
	v_writelane_b32 v249, s6, 4
	s_addc_u32 s5, s67, s7
	v_cmp_eq_u32_e64 s[8:9], 0, v203
	v_writelane_b32 v249, s7, 5
	s_add_u32 s6, s4, 0x100000
	s_addc_u32 s7, s5, 0
	s_add_u32 s4, s66, 0x38f8400
	v_writelane_b32 v249, s4, 6
	s_addc_u32 s4, s67, 0
	v_writelane_b32 v249, s4, 8
	s_lshl_b32 s4, s52, 10
	s_mov_b32 s5, s69
	v_writelane_b32 v249, s4, 9
	s_mul_i32 s16, s52, 0x300
	s_mov_b32 s17, s69
	v_writelane_b32 v249, s5, 10
	s_add_u32 s4, s66, 0x2df8400
	v_writelane_b32 v249, s4, 11
	s_addc_u32 s4, s67, 0
	v_writelane_b32 v249, s4, 13
	s_lshl_b32 s4, s52, 22
	v_writelane_b32 v249, s4, 15
	s_add_u32 s4, s66, 0x2bf8400
	v_writelane_b32 v249, s4, 17
	s_addc_u32 s4, s67, 0
	v_writelane_b32 v249, s4, 19
	s_lshl_b32 s4, s52, 20
	v_writelane_b32 v249, s4, 21
	s_add_u32 s4, s66, 0x2b78400
	v_writelane_b32 v249, s4, 23
	s_addc_u32 s4, s67, 0
	v_writelane_b32 v249, s4, 25
	s_add_u32 s4, s66, 0x29f8400
	v_writelane_b32 v249, s4, 27
	s_addc_u32 s4, s67, 0
	v_writelane_b32 v249, s4, 28
	s_add_u32 s4, s66, 0x2878400
	v_writelane_b32 v249, s4, 30
	s_addc_u32 s4, s67, 0
	s_add_u32 s14, s66, 0xea78400
	s_addc_u32 s15, s67, 0
	v_writelane_b32 v249, s4, 31
	s_add_u32 s4, s66, 0x2608400
	v_writelane_b32 v249, s4, 32
	s_addc_u32 s4, s67, 0
	v_writelane_b32 v249, s4, 33
	s_add_u32 s4, s66, 0x1c8400
	s_addc_u32 s5, s67, 0
	v_writelane_b32 v249, s4, 34
	s_nop 1
	v_writelane_b32 v249, s5, 35
	s_add_u32 s4, s66, 0x288400
	s_addc_u32 s5, s67, 0
	v_writelane_b32 v249, s4, 36
	s_nop 1
	v_writelane_b32 v249, s5, 37
	s_add_u32 s4, s66, 0x7678400
	s_addc_u32 s5, s67, 0
	v_writelane_b32 v249, s4, 38
	s_nop 1
	v_writelane_b32 v249, s5, 39
	s_add_u32 s4, s66, 0x8e78400
	s_addc_u32 s5, s67, 0
	s_add_u32 s61, s66, 0x408400
	s_addc_u32 s78, s67, 0
	s_add_u32 s79, s66, 0x100400
	v_writelane_b32 v249, s4, 40
	s_addc_u32 s86, s67, 0
	s_nop 0
	v_writelane_b32 v249, s5, 41
	s_add_u32 s4, s66, 0x3a8400
	v_writelane_b32 v249, s4, 42
	s_addc_u32 s4, s67, 0
	s_add_u32 s89, s66, 0x348400
	s_addc_u32 s90, s67, 0
	v_writelane_b32 v249, s4, 43
	s_branch .LBB0_553

.LBB0_553:
	s_barrier
	s_and_saveexec_b64 s[10:11], s[8:9]
	s_cbranch_execz .LBB0_557
	s_mov_b64 s[28:29], exec
	v_mbcnt_lo_u32_b32 v0, s28, 0
	v_mbcnt_hi_u32_b32 v0, s29, v0
	v_cmp_eq_u32_e32 vcc, 0, v0
	s_and_saveexec_b64 s[26:27], vcc
	s_cbranch_execz .LBB0_556
	s_bcnt1_i32_b64 s4, s[28:29]
	v_mov_b32_e32 v2, s4
	global_atomic_add v2, v1, v2, s[6:7] sc0
.LBB0_556:
	s_or_b64 exec, exec, s[26:27]
	s_waitcnt vmcnt(0)
	v_readfirstlane_b32 s4, v2
	v_mov_b32_e32 v2, s71
	s_nop 0
	v_add_u32_e32 v0, s4, v0
	ds_write_b32 v2, v0

.LBB0_656:
	s_andn2_b64 vcc, exec, s[10:11]
	s_cbranch_vccnz .LBB0_789
	s_add_i32 s10, s91, 0xffffff40
	v_mov_b32_e32 v4, v203
	s_lshl_b32 s42, s10, 6
	v_ashrrev_i32_e32 v5, 3, v4
	v_add_u32_e32 v0, s42, v5
	v_mov_b64_e32 v[2:3], s[14:15]
	v_readfirstlane_b32 s11, v4
	v_mad_i64_i32 v[2:3], s[4:5], v0, s63, v[2:3]
	v_lshlrev_b32_e32 v0, 4, v4
	s_ashr_i32 s5, s11, 5
	s_ashr_i32 s12, s11, 6
	v_and_b32_e32 v0, 0x70, v0
	s_movk_i32 s4, 0x310
	s_and_b32 s26, s5, -8
	v_and_b32_e32 v6, 63, v4
	v_lshl_add_u64 v[8:9], v[2:3], 0, v[0:1]
	s_movk_i32 s68, 0x1f80
	v_lshl_add_u64 v[70:71], s[68:69], 1, v[8:9]
	global_load_dwordx4 v[72:75], v[70:71], off
	global_load_dwordx4 v[76:79], v[70:71], off offset:128
	global_load_dwordx4 v[80:83], v[70:71], off offset:256
	v_bfe_u32 v84, v4, 8, 1
	v_lshlrev_b32_e32 v84, 12, v84
	v_bfe_u32 v85, v4, 5, 1
	v_lshl_or_b32 v84, v85, 11, v84
	v_bfe_u32 v85, v4, 2, 1
	v_lshl_or_b32 v84, v85, 10, v84
	v_and_b32_e32 v85, 3, v4
	v_lshl_or_b32 v84, v85, 8, v84
	v_bfe_u32 v85, v4, 6, 2
	v_lshl_or_b32 v84, v85, 6, v84
	v_bfe_u32 v85, v4, 3, 2
	v_lshl_or_b32 v84, v85, 4, v84
	v_lshl_add_u32 v84, s10, 13, v84
	v_mov_b32_e32 v85, 0
	v_lshl_add_u64 v[84:85], s[66:67], 0, v[84:85]
	v_add_co_u32_e32 v84, vcc, 0x3e78400, v84
	s_nop 1
	v_addc_co_u32_e32 v85, vcc, 0, v85, vcc
	v_lshrrev_b32_e32 v86, 4, v6
	v_lshlrev_b32_e32 v86, 11, v86
	v_and_b32_e32 v87, 15, v6
	v_lshl_or_b32 v86, v87, 4, v86
	v_lshrrev_b32_e32 v87, 8, v4
	v_lshl_add_u32 v86, v87, 10, v86
	v_bfe_u32 v87, v4, 6, 2
	v_lshl_add_u32 v86, v87, 8, v86
	v_lshl_add_u32 v86, s10, 13, v86
	v_mov_b32_e32 v87, 0
	v_lshl_add_u64 v[86:87], s[66:67], 0, v[86:87]
	v_add_co_u32_e32 v86, vcc, 0x4478400, v86
	s_nop 1
	v_addc_co_u32_e32 v87, vcc, 0, v87, vcc
	v_mul_lo_u32 v2, v5, s4
	s_and_b32 s4, s12, 3
	s_lshl_b32 s11, s12, 12
	s_lshl_b32 s45, s10, 4
	s_lshl_b32 s46, s10, 2
	s_lshl_b32 s10, s26, 2
	s_lshl_b32 s5, s5, 2
	v_add_u32_e32 v5, 0, v2
	s_lshl_b32 s28, s12, 3
	s_lshl_b32 s88, s12, 1
	v_lshlrev_b32_e32 v2, 15, v6
	s_and_b32 s44, s11, 0x3000
	s_lshl_b32 s30, s12, 11
	s_or_b32 s47, s10, s4
	s_or_b32 s4, s5, s4
	v_mov_b32_e32 v3, v1
	s_mov_b64 s[10:11], 0xc878400
	s_mov_b32 s54, 1
	v_lshl_add_u32 v11, v6, 1, 0
	v_add_u32_e32 v10, 0xc678400, v2
	s_ashr_i32 s27, s26, 31
	s_ashr_i32 s29, s28, 31
	s_ashr_i32 s31, s30, 31
	s_or_b32 s48, s47, 4
	s_or_b32 s49, s28, 1
	s_or_b32 s50, s47, 8
	s_or_b32 s51, s28, 2
	s_or_b32 s53, s47, 12
	s_or_b32 s55, s28, 3
	s_or_b32 s56, s47, 16
	s_or_b32 s57, s28, 4
	s_or_b32 s58, s47, 20
	s_or_b32 s59, s28, 5
	s_or_b32 s60, s47, 24
	s_or_b32 s12, s28, 6
	s_or_b32 s13, s4, 28
	s_or_b32 s18, s28, 7
	s_add_i32 s87, s88, 16
	s_add_i32 s20, s88, 32
	s_add_i32 s21, s88, 48
	s_or_b32 s4, s88, 1
	s_add_i32 s5, s88, 17
	s_add_i32 s22, s88, 33
	s_add_i32 s23, s88, 49
	v_add_u32_e32 v12, 0xca78400, v2
	v_add_u32_e32 v14, 0xcc78400, v2
	v_add_u32_e32 v16, 0xce78400, v2
	v_add_u32_e32 v18, 0xd078400, v2
	v_or_b32_e32 v20, 0xffffffc0, v4
	v_mov_b32_e32 v7, v1
	v_or_b32_e32 v22, 0xfffffe80, v6
	s_mov_b32 s24, 0
	v_or_b32_e32 v24, 0xffffff80, v6
	v_lshl_add_u64 v[26:27], v[2:3], 0, s[10:11]
	s_mov_b64 s[34:35], 0
	v_add_u32_e32 v13, v5, v0
	s_waitcnt vmcnt(0)
	global_store_dwordx4 v[84:85], v[72:75], off
	v_add_co_u32_e32 v88, vcc, 0x200000, v84
	s_nop 1
	v_addc_co_u32_e32 v89, vcc, 0, v85, vcc
	global_store_dwordx4 v[88:89], v[76:79], off
	v_add_co_u32_e32 v88, vcc, 0x400000, v84
	s_nop 1
	v_addc_co_u32_e32 v89, vcc, 0, v85, vcc
	global_store_dwordx4 v[88:89], v[80:83], off
	s_branch .LBB0_659

.LBB0_661:
	s_andn2_b64 vcc, exec, s[40:41]
	s_cbranch_vccnz .LBB0_663
	s_lshl_b32 s68, s42, 1
	v_lshl_add_u64 v[28:29], v[28:29], 0, s[68:69]
	v_lshl_add_u64 v[28:29], s[28:29], 1, v[28:29]
	global_store_dwordx4 v[28:29], v[2:5], off
	s_mul_i32 s68, s24, 0x600000
	v_lshl_add_u64 v[90:91], v[86:87], 0, s[68:69]
	global_store_dwordx4 v[90:91], v[2:5], off

.LBB0_667:
	s_andn2_b64 vcc, exec, s[38:39]
	s_mov_b32 s25, s23
	s_mov_b32 s38, s22
	s_mov_b32 s39, s5
	s_mov_b32 s40, s4
	s_mov_b32 s41, s21
	s_mov_b32 s68, s20
	s_mov_b32 s19, s87
	s_mov_b32 s43, s88
	s_cbranch_vccnz .LBB0_669
	s_lshl_b32 s68, s42, 1
	v_lshl_add_u64 v[28:29], v[28:29], 0, s[68:69]
	v_lshl_add_u64 v[28:29], s[28:29], 1, v[28:29]
	s_mul_i32 s68, s24, 0x600000
	s_add_i32 s68, s68, 0x200000
	v_lshl_add_u64 v[90:91], v[86:87], 0, s[68:69]
	global_store_dwordx4 v[90:91], v[2:5], off
	s_mov_b32 s25, s18
	s_mov_b32 s38, s12
	s_mov_b32 s39, s59
	s_mov_b32 s40, s57
	s_mov_b32 s41, s55
	s_mov_b32 s68, s51
	s_mov_b32 s19, s49
	s_mov_b32 s43, s28
	global_store_dwordx4 v[28:29], v[2:5], off

.LBB0_671:
	s_andn2_b64 vcc, exec, s[38:39]
	s_cbranch_vccnz .LBB0_673
	s_lshl_b32 s68, s42, 1
	v_lshl_add_u64 v[30:31], v[30:31], 0, s[68:69]
	v_lshl_add_u64 v[30:31], s[28:29], 1, v[30:31]
	global_store_dwordx4 v[30:31], v[2:5], off
	s_mul_i32 s68, s24, 0x600000
	s_add_i32 s68, s68, 0x400000
	v_lshl_add_u64 v[90:91], v[86:87], 0, s[68:69]
	global_store_dwordx4 v[90:91], v[2:5], off

.LBB0_854:
	s_or_b64 exec, exec, s[6:7]
	s_add_i32 s6, s52, 1
	s_cmp_eq_u32 s52, 3
	s_movk_i32 s4, 0x960
	s_cselect_b32 s22, s4, 0xdfb
	v_readlane_b32 s4, v249, 4
	s_waitcnt lgkmcnt(0)
	s_barrier
	v_readlane_b32 s5, v249, 5
	s_add_u32 s4, s66, s4
	s_addc_u32 s5, s67, s5
	s_add_u32 s20, s4, 0x100004
	s_addc_u32 s21, s5, 0
	s_add_u32 s4, s66, 0x100400
	s_addc_u32 s5, s67, 0
	v_writelane_b32 v249, s4, 44
	s_lshl_b32 s17, s6, 16
	v_bfe_u32 v2, v203, 4, 2
	v_writelane_b32 v249, s5, 45
	s_add_u32 s4, s66, 0x2870400
	v_writelane_b32 v249, s4, 46
	s_addc_u32 s4, s67, 0
	v_writelane_b32 v249, s4, 47
	s_add_u32 s4, s66, 0x2868400
	v_writelane_b32 v249, s4, 48
	s_addc_u32 s4, s67, 0
	v_writelane_b32 v249, s4, 49
	s_lshl_b32 s4, s6, 21
	v_writelane_b32 v249, s4, 50
	s_add_u32 s4, s66, 0x2768400
	v_writelane_b32 v249, s4, 51
	s_addc_u32 s4, s67, 0
	v_writelane_b32 v249, s4, 52
	s_add_u32 s4, s66, 0x2668400
	v_writelane_b32 v249, s4, 53
	s_addc_u32 s4, s67, 0
	v_writelane_b32 v249, s4, 54
	s_mul_i32 s4, s6, 0x60000
	v_writelane_b32 v249, s4, 55
	s_add_u32 s4, s66, 0x2608400
	v_writelane_b32 v249, s4, 56
	s_addc_u32 s4, s67, 0
	v_writelane_b32 v249, s4, 57
	s_add_u32 s4, s66, 0x408400
	v_writelane_b32 v249, s4, 58
	s_addc_u32 s4, s67, 0
	v_writelane_b32 v249, s4, 59
	s_lshl_b32 s4, s6, 10
	s_mov_b32 s5, s69
	v_writelane_b32 v249, s4, 60
	v_ashrrev_i32_e32 v0, 6, v203
	v_and_b32_e32 v205, 15, v203
	v_writelane_b32 v249, s5, 61
	s_add_u32 s4, s66, 0x1488400
	v_writelane_b32 v249, s4, 62
	s_addc_u32 s4, s67, 0
	v_writelane_b32 v249, s4, 63
	s_mul_i32 s4, s6, 0xb00000
	v_writelane_b32 v248, s4, 0
	s_add_u32 s4, s66, 0xf08400
	v_writelane_b32 v248, s4, 1
	s_addc_u32 s4, s67, 0
	v_lshlrev_b32_e32 v160, 2, v2
	v_writelane_b32 v248, s4, 2
	v_add_u32_e32 v204, 0xffffe500, v0
	v_lshlrev_b32_e32 v0, 3, v2
	v_sub_u32_e32 v2, v160, v205
	s_movk_i32 s4, 0x81
	v_writelane_b32 v249, s6, 8
	v_cmp_gt_u32_e64 s[6:7], s4, v2
	v_add_u32_e32 v4, 1, v2
	s_add_u32 s88, s66, 0xea78400
	v_writelane_b32 v249, s6, 28
	s_addc_u32 s89, s67, 0
	v_and_b32_e32 v3, 63, v203
	v_writelane_b32 v249, s7, 29
	v_cmp_gt_u32_e64 s[6:7], s4, v4
	v_add_u32_e32 v4, 2, v2
	v_or_b32_e32 v206, 0xffffff90, v205
	v_writelane_b32 v249, s6, 21
	v_or_b32_e32 v207, 0xffffffb0, v205
	v_or_b32_e32 v208, 0xffffffd0, v205
	v_writelane_b32 v249, s7, 22
	v_cmp_gt_u32_e64 s[6:7], s4, v4
	v_add_u32_e32 v4, 3, v2
	v_or_b32_e32 v209, -16, v203
	v_writelane_b32 v249, s6, 23
	v_or_b32_e32 v210, 16, v160
	v_lshlrev_b32_e32 v162, 1, v0
	v_writelane_b32 v249, s7, 24
	v_cmp_gt_u32_e64 s[6:7], s4, v4
	v_add_u32_e32 v4, 0x80, v2
	s_nop 0
	v_writelane_b32 v249, s6, 25
	s_nop 1
	v_writelane_b32 v249, s7, 26
	v_cmp_gt_u32_e64 s[6:7], s4, v4
	v_add_u32_e32 v4, 0x82, v2
	s_nop 0
	v_writelane_b32 v249, s6, 15
	s_nop 1
	v_writelane_b32 v249, s7, 16
	v_cmp_lt_u32_e64 s[6:7], 12, v2
	v_add_u32_e32 v2, 0x83, v2
	s_nop 0
	v_writelane_b32 v249, s6, 17
	s_nop 1
	v_writelane_b32 v249, s7, 18
	v_cmp_gt_u32_e64 s[6:7], s4, v4
	v_cmp_gt_u32_e64 s[4:5], s4, v2
	v_lshlrev_b32_e32 v2, 14, v205
	v_writelane_b32 v249, s6, 19
	v_lshlrev_b32_e32 v164, 1, v2
	s_nop 0
	v_writelane_b32 v249, s7, 20
	v_writelane_b32 v249, s4, 9
	s_nop 1
	v_writelane_b32 v249, s5, 10
	s_add_u32 s4, s66, 0xd278400
	s_addc_u32 s5, s67, 0
	v_writelane_b32 v249, s4, 11
	s_nop 1
	v_writelane_b32 v249, s5, 12
	v_cmp_gt_u32_e64 s[4:5], 16, v3
	s_nop 1
	v_writelane_b32 v249, s4, 13
	s_nop 1
	v_writelane_b32 v249, s5, 14
	s_add_u32 s4, s66, 0x108400
	s_addc_u32 s5, s67, 0
	v_writelane_b32 v248, s4, 3
	s_nop 1
	v_writelane_b32 v248, s5, 4
	s_add_u32 s4, s66, 0x3a8400
	v_writelane_b32 v249, s4, 42
	s_addc_u32 s4, s67, 0
	v_writelane_b32 v249, s4, 43
	s_add_u32 s4, s66, 0x348400
	v_writelane_b32 v249, s4, 32
	s_addc_u32 s4, s67, 0
	s_add_u32 s18, s66, 0xa678400
	s_addc_u32 s19, s67, 0
	v_writelane_b32 v249, s4, 33
	s_add_u32 s4, s66, 0xea7c300
	v_writelane_b32 v249, s4, 38
	s_addc_u32 s4, s67, 0
	v_writelane_b32 v249, s4, 40
	s_add_u32 s4, s66, 0xc678400
	v_writelane_b32 v249, s4, 4
	s_addc_u32 s4, s67, 0
	v_writelane_b32 v249, s4, 34
	s_add_u32 s4, s66, 0xea7c600
	v_writelane_b32 v249, s4, 36
	s_addc_u32 s4, s67, 0
	v_writelane_b32 v249, s4, 30
	s_add_u32 s4, s66, 0xcc78400
	v_writelane_b32 v249, s4, 31
	s_addc_u32 s4, s67, 0
	s_add_u32 s86, s66, 0x7678400
	s_addc_u32 s87, s67, 0
	v_writelane_b32 v249, s4, 27
	s_add_u32 s4, s66, 0x8e78400
	s_addc_u32 s5, s67, 0
	s_add_u32 s90, s66, 0x5e78400
	s_addc_u32 s91, s67, 0
	s_add_u32 s6, s66, 0x25da400
	s_addc_u32 s7, s67, 0
	v_writelane_b32 v248, s6, 5
	s_nop 1
	v_writelane_b32 v248, s7, 6
	s_add_u32 s6, s66, 0x288400
	s_addc_u32 s7, s67, 0
	s_add_u32 s15, s66, 0x1c8400
	v_writelane_b32 v249, s6, 6
	s_addc_u32 s23, s67, 0
	s_nop 0
	v_writelane_b32 v249, s7, 7
	s_branch .LBB0_857

.LBB0_857:
	s_barrier
	s_and_saveexec_b64 s[28:29], s[8:9]
	s_cbranch_execz .LBB0_861
	s_mov_b64 s[30:31], exec
	v_mbcnt_lo_u32_b32 v0, s30, 0
	v_mbcnt_hi_u32_b32 v0, s31, v0
	v_cmp_eq_u32_e32 vcc, 0, v0
	s_and_saveexec_b64 s[6:7], vcc
	s_cbranch_execz .LBB0_860
	s_bcnt1_i32_b64 s10, s[30:31]
	v_mov_b32_e32 v2, s10
	global_atomic_add v2, v1, v2, s[20:21] sc0
.LBB0_860:
	s_or_b64 exec, exec, s[6:7]
	s_waitcnt vmcnt(0)
	v_readfirstlane_b32 s6, v2
	v_mov_b32_e32 v2, s71
	s_nop 0
	v_add_u32_e32 v0, s6, v0
	ds_write_b32 v2, v0

.LBB0_1157:
	s_cmp_gt_u32 s79, 63
	s_cselect_b32 s50, s78, 8
	s_cmp_ge_i32 s50, s25
	s_waitcnt lgkmcnt(0)
	s_barrier
	s_cbranch_scc1 .LBB0_1211
	s_add_i32 s6, 0, 0x20000
	v_lshl_add_u32 v227, v74, 5, s6
	v_cmp_lt_u32_e64 s[30:31], 3, v75
	v_cmp_eq_u32_e64 s[34:35], 1, v217
	v_cmp_eq_u32_e64 s[36:37], 2, v217
	s_lshl_b32 s6, s68, 21
	v_lshl_add_u32 v182, v197, 4, s6
	v_add_u32_e32 v182, 0x1000, v182
	v_mov_b32_e32 v183, 0
	v_lshl_add_u64 v[182:183], s[66:67], 0, v[182:183]
	s_mov_b64 s[6:7], 0x3e78400
	v_lshl_add_u64 v[182:183], v[182:183], 0, s[6:7]
	s_mov_b64 s[6:7], 0x600000
	v_lshl_add_u64 v[184:185], v[182:183], 0, s[6:7]
	s_branch .LBB0_1160

.LBB0_1160:
	s_lshl_b32 s6, s50, 13
	s_mov_b32 s7, 0
	s_waitcnt vmcnt(0)
	v_lshl_add_u64 v[30:31], v[182:183], 0, s[6:7]
	v_lshl_add_u64 v[62:63], v[184:185], 0, s[6:7]
	global_load_dwordx4 v[2:5], v[30:31], off offset:-4096
	global_load_dwordx4 v[6:9], v[30:31], off offset:-3072
	global_load_dwordx4 v[10:13], v[30:31], off offset:-2048
	global_load_dwordx4 v[14:17], v[30:31], off offset:-1024
	global_load_dwordx4 v[18:21], v[30:31], off
	global_load_dwordx4 v[22:25], v[30:31], off offset:1024
	global_load_dwordx4 v[26:29], v[30:31], off offset:2048
	global_load_dwordx4 v[30:33], v[30:31], off offset:3072
	global_load_dwordx4 v[34:37], v[62:63], off offset:-4096
	global_load_dwordx4 v[38:41], v[62:63], off offset:-3072
	global_load_dwordx4 v[42:45], v[62:63], off offset:-2048
	global_load_dwordx4 v[46:49], v[62:63], off offset:-1024
	global_load_dwordx4 v[50:53], v[62:63], off
	global_load_dwordx4 v[54:57], v[62:63], off offset:1024
	global_load_dwordx4 v[58:61], v[62:63], off offset:2048
	global_load_dwordx4 v[62:65], v[62:63], off offset:3072
	s_add_i32 s10, s50, 8
	s_cmp_ge_i32 s10, s25
	s_mov_b64 s[6:7], -1
	s_cbranch_scc0 .LBB0_1163
	s_ashr_i32 s6, s50, 5
	v_lshl_add_u32 v0, s6, 2, v227
	ds_read_b32 v0, v0
	s_and_b32 s6, s50, 31
	s_waitcnt lgkmcnt(0)
	v_bfe_u32 v0, v0, s6, 1
	v_cmp_ne_u32_e32 vcc, 0, v0
	s_cbranch_vccnz .LBB0_1166

.LBB0_1163:
	s_andn2_b64 vcc, exec, s[6:7]
	s_cbranch_vccnz .LBB0_1159
	s_lshl_b32 s6, s10, 13
	s_mov_b32 s7, 0
	v_lshl_add_u64 v[94:95], v[182:183], 0, s[6:7]
	v_lshl_add_u64 v[126:127], v[184:185], 0, s[6:7]
	global_load_dwordx4 v[66:69], v[94:95], off offset:-4096
	global_load_dwordx4 v[70:73], v[94:95], off offset:-3072
	global_load_dwordx4 v[74:77], v[94:95], off offset:-2048
	global_load_dwordx4 v[78:81], v[94:95], off offset:-1024
	global_load_dwordx4 v[82:85], v[94:95], off
	global_load_dwordx4 v[86:89], v[94:95], off offset:1024
	global_load_dwordx4 v[90:93], v[94:95], off offset:2048
	global_load_dwordx4 v[94:97], v[94:95], off offset:3072
	global_load_dwordx4 v[98:101], v[126:127], off offset:-4096
	global_load_dwordx4 v[102:105], v[126:127], off offset:-3072
	global_load_dwordx4 v[106:109], v[126:127], off offset:-2048
	global_load_dwordx4 v[110:113], v[126:127], off offset:-1024
	global_load_dwordx4 v[114:117], v[126:127], off
	global_load_dwordx4 v[118:121], v[126:127], off offset:1024
	global_load_dwordx4 v[122:125], v[126:127], off offset:2048
	global_load_dwordx4 v[126:129], v[126:127], off offset:3072
	s_ashr_i32 s6, s50, 5
	v_lshl_add_u32 v0, s6, 2, v227
	ds_read_b32 v0, v0
	s_and_b32 s6, s50, 31
	s_waitcnt lgkmcnt(0)
	v_bfe_u32 v0, v0, s6, 1
	s_ashr_i32 s6, s10, 5
	v_cmp_ne_u32_e64 s[42:43], 0, v0
	v_lshl_add_u32 v0, s6, 2, v227
	ds_read_b32 v0, v0
	s_and_b32 s6, s10, 31
	s_cmp_eq_u64 s[42:43], 0
	s_waitcnt lgkmcnt(0)
	v_bfe_u32 v0, v0, s6, 1
	v_cmp_ne_u32_e64 s[46:47], 0, v0
	s_cselect_b64 s[6:7], -1, 0
	s_cmp_eq_u64 s[46:47], 0
	s_cselect_b64 s[10:11], -1, 0
	s_or_b64 s[6:7], s[6:7], s[10:11]
	s_and_b64 vcc, exec, s[6:7]
	s_cbranch_vccz .LBB0_1175
	s_branch .LBB0_1192

	.amdhsa_kernel _Z4mega4Args
		.amdhsa_group_segment_fixed_size 0
		.amdhsa_private_segment_fixed_size 0
		.amdhsa_kernarg_size 504
		.amdhsa_user_sgpr_count 2
		.amdhsa_user_sgpr_dispatch_ptr 0
		.amdhsa_user_sgpr_queue_ptr 0
		.amdhsa_user_sgpr_kernarg_segment_ptr 1
		.amdhsa_user_sgpr_dispatch_id 0
		.amdhsa_user_sgpr_kernarg_preload_length 0
		.amdhsa_user_sgpr_kernarg_preload_offset 0
		.amdhsa_user_sgpr_private_segment_size 0
		.amdhsa_uses_dynamic_stack 0
		.amdhsa_enable_private_segment 0
		.amdhsa_system_sgpr_workgroup_id_x 1
		.amdhsa_system_sgpr_workgroup_id_y 0
		.amdhsa_system_sgpr_workgroup_id_z 0
		.amdhsa_system_sgpr_workgroup_info 0
		.amdhsa_system_vgpr_workitem_id 2
		.amdhsa_next_free_vgpr 251
		.amdhsa_next_free_sgpr 100
		.amdhsa_accum_offset 252
		.amdhsa_reserve_vcc 1
		.amdhsa_float_round_mode_32 0
		.amdhsa_float_round_mode_16_64 0
		.amdhsa_float_denorm_mode_32 3
		.amdhsa_float_denorm_mode_16_64 3
		.amdhsa_dx10_clamp 1
		.amdhsa_ieee_mode 1
		.amdhsa_fp16_overflow 0
		.amdhsa_tg_split 0
		.amdhsa_exception_fp_ieee_invalid_op 0
		.amdhsa_exception_fp_denorm_src 0
		.amdhsa_exception_fp_ieee_div_zero 0
		.amdhsa_exception_fp_ieee_overflow 0
		.amdhsa_exception_fp_ieee_underflow 0
		.amdhsa_exception_fp_ieee_inexact 0
		.amdhsa_exception_int_div_zero 0
	.end_amdhsa_kernel

amdhsa.kernels:
  - .agpr_count:     0
    .args:
      - .offset:         0
        .size:           248
        .value_kind:     by_value
      - .offset:         248
        .size:           4
        .value_kind:     hidden_block_count_x
      - .offset:         252
        .size:           4
        .value_kind:     hidden_block_count_y
      - .offset:         256
        .size:           4
        .value_kind:     hidden_block_count_z
      - .offset:         260
        .size:           2
        .value_kind:     hidden_group_size_x
      - .offset:         262
        .size:           2
        .value_kind:     hidden_group_size_y
      - .offset:         264
        .size:           2
        .value_kind:     hidden_group_size_z
      - .offset:         266
        .size:           2
        .value_kind:     hidden_remainder_x
      - .offset:         268
        .size:           2
        .value_kind:     hidden_remainder_y
      - .offset:         270
        .size:           2
        .value_kind:     hidden_remainder_z
      - .offset:         288
        .size:           8
        .value_kind:     hidden_global_offset_x
      - .offset:         296
        .size:           8
        .value_kind:     hidden_global_offset_y
      - .offset:         304
        .size:           8
        .value_kind:     hidden_global_offset_z
      - .offset:         312
        .size:           2
        .value_kind:     hidden_grid_dims
      - .offset:         336
        .size:           8
        .value_kind:     hidden_multigrid_sync_arg
      - .offset:         368
        .size:           4
        .value_kind:     hidden_dynamic_lds_size
    .group_segment_fixed_size: 0
    .kernarg_segment_align: 8
    .kernarg_segment_size: 504
    .language:       OpenCL C
    .language_version:
      - 2
      - 0
    .max_flat_workgroup_size: 512
    .name:           _Z4mega4Args
    .private_segment_fixed_size: 0
    .sgpr_count:     106
    .sgpr_spill_count: 164
    .symbol:         _Z4mega4Args.kd
    .uniform_work_group_size: 1
    .uses_dynamic_stack: false
    .vgpr_count:     251
    .vgpr_spill_count: 0
    .wavefront_size: 64
